# P4 and P10 epilogues: per-row rstd (IEEE sqrt+div, bit-identical) computed once per wave lane-distributed and broadcast by ds_bpermute instead of 8x redundantly per lane; conv nw loads batched
# speedup vs baseline: 1.0058x; 1.0058x over previous
; template <int RSM> __device__ __forceinline__ float row_scale(const float* p, int row) { const float v = __hip_atomic_load(p + row, __ATOMIC_RELAXED, __HIP_MEMORY_SCOPE_AGENT); return RSM == 0 ? v : 1.0f / sqrtf(v * (1.f / DM) + EPS); }
;     __device__ __forceinline__ void operator()(const f32x4 (&acc)[2][2][4][2], const Unit& u, int wr, int wc, int fr, int fq) const {
;     ...
;             for (int m = 0; m < 4; ++m) { const int row = row0 + ai * HALF + m * 16; const float sc = row_scale<1>(rs, row);
;                 f32x4 c0, c1, s0, s1;
;                 if (rope) { const int pos = row & (SEQ - 1); c0 = *(const f32x4*)(ropeC + pos * 8); c1 = *(const f32x4*)(ropeC + pos * 8 + 4); s0 = *(const f32x4*)(ropeS + pos * 8); s1 = *(const f32x4*)(ropeS + pos * 8 + 4); }
; #pragma unroll
;                 for (int bj = 0; bj < 2; ++bj) { const f32x4 a0 = acc[ai][bj][m][0] * sc, a1 = acc[ai][bj][m][1] * sc;
.LBB0_268:
	v_lshl_add_u32 v180, s10, 8, v205
	v_ashrrev_i32_e32 v181, 31, v180
	v_lshl_add_u64 v[182:183], v[180:181], 2, s[88:89]
	global_load_dword v245, v[182:183], off sc1
	global_load_dword v246, v[182:183], off offset:64 sc1
	global_load_dword v247, v[182:183], off offset:128 sc1
	global_load_dword v248, v[182:183], off offset:192 sc1
	global_load_dword v249, v[182:183], off offset:512 sc1
	global_load_dword v251, v[182:183], off offset:576 sc1
	global_load_dword v252, v[182:183], off offset:640 sc1
	global_load_dword v253, v[182:183], off offset:704 sc1
	v_bfe_u32 v187, v222, 4, 1
	v_cmp_ne_u32_e64 s[98:99], 0, v187
	v_bfe_u32 v187, v222, 5, 1
	v_cmp_ne_u32_e64 s[100:101], 0, v187
	v_and_b32_e32 v215, 15, v222
	v_lshlrev_b32_e32 v215, 2, v215
	s_waitcnt vmcnt(0)
	v_cndmask_b32_e64 v245, v245, v247, s[98:99]
	v_cndmask_b32_e64 v249, v249, v252, s[98:99]
	v_cndmask_b32_e64 v245, v245, v249, s[100:101]
	v_cndmask_b32_e64 v246, v246, v248, s[98:99]
	v_cndmask_b32_e64 v251, v251, v253, s[98:99]
	v_cndmask_b32_e64 v246, v246, v251, s[100:101]
	v_fmamk_f32 v245, v245, 0x3a000000, v211
	v_mul_f32_e32 v187, 0x4f800000, v245
	v_cmp_gt_f32_e32 vcc, s56, v245
	s_nop 1
	v_cndmask_b32_e32 v245, v245, v187, vcc
	v_sqrt_f32_e32 v186, v245
	s_nop 0
	v_add_u32_e32 v188, -1, v186
	v_add_u32_e32 v189, 1, v186
	v_fma_f32 v190, -v188, v186, v245
	v_fma_f32 v191, -v189, v186, v245
	v_cmp_ge_f32_e64 s[98:99], 0, v190
	s_nop 1
	v_cndmask_b32_e64 v186, v186, v188, s[98:99]
	v_cmp_lt_f32_e64 s[98:99], 0, v191
	s_nop 1
	v_cndmask_b32_e64 v186, v186, v189, s[98:99]
	v_mul_f32_e32 v188, 0x37800000, v186
	v_cndmask_b32_e32 v186, v186, v188, vcc
	v_cmp_class_f32_e32 vcc, v245, v212
	s_nop 1
	v_cndmask_b32_e32 v245, v186, v245, vcc
	v_div_scale_f32 v189, s[100:101], v245, v245, 1.0
	v_rcp_f32_e32 v190, v189
	v_div_scale_f32 v187, vcc, 1.0, v245, 1.0
	v_fma_f32 v191, -v189, v190, 1.0
	v_fmac_f32_e32 v190, v191, v190
	v_mul_f32_e32 v191, v187, v190
	v_fma_f32 v227, -v189, v191, v187
	v_fmac_f32_e32 v191, v227, v190
	v_fma_f32 v187, -v189, v191, v187
	v_div_fmas_f32 v187, v187, v190, v191
	v_div_fixup_f32 v245, v187, v245, 1.0
	v_fmamk_f32 v246, v246, 0x3a000000, v211
	v_mul_f32_e32 v187, 0x4f800000, v246
	v_cmp_gt_f32_e32 vcc, s56, v246
	s_nop 1
	v_cndmask_b32_e32 v246, v246, v187, vcc
	v_sqrt_f32_e32 v186, v246
	s_nop 0
	v_add_u32_e32 v188, -1, v186
	v_add_u32_e32 v189, 1, v186
	v_fma_f32 v190, -v188, v186, v246
	v_fma_f32 v191, -v189, v186, v246
	v_cmp_ge_f32_e64 s[98:99], 0, v190
	s_nop 1
	v_cndmask_b32_e64 v186, v186, v188, s[98:99]
	v_cmp_lt_f32_e64 s[98:99], 0, v191
	s_nop 1
	v_cndmask_b32_e64 v186, v186, v189, s[98:99]
	v_mul_f32_e32 v188, 0x37800000, v186
	v_cndmask_b32_e32 v186, v186, v188, vcc
	v_cmp_class_f32_e32 vcc, v246, v212
	s_nop 1
	v_cndmask_b32_e32 v246, v186, v246, vcc
	v_div_scale_f32 v189, s[100:101], v246, v246, 1.0
	v_rcp_f32_e32 v190, v189
	v_div_scale_f32 v187, vcc, 1.0, v246, 1.0
	v_fma_f32 v191, -v189, v190, 1.0
	v_fmac_f32_e32 v190, v191, v190
	v_mul_f32_e32 v191, v187, v190
	v_fma_f32 v227, -v189, v191, v187
	v_fmac_f32_e32 v191, v227, v190
	v_fma_f32 v187, -v189, v191, v187
	v_div_fmas_f32 v187, v187, v190, v191
	v_div_fixup_f32 v246, v187, v246, 1.0
	ds_bpermute_b32 v247, v215, v245
	ds_bpermute_b32 v248, v215, v246
	ds_bpermute_b32 v249, v215, v245 offset:64
	ds_bpermute_b32 v251, v215, v246 offset:64
	ds_bpermute_b32 v252, v215, v245 offset:128
	ds_bpermute_b32 v253, v215, v246 offset:128
	ds_bpermute_b32 v254, v215, v245 offset:192
	ds_bpermute_b32 v255, v215, v246 offset:192
	s_waitcnt lgkmcnt(0)
	s_cmp_gt_i32 s6, 1
	s_cselect_b64 s[16:17], -1, 0
	s_cmp_lt_i32 s6, 2
	s_cselect_b64 s[0:1], -1, 0
	s_and_b64 s[0:1], s[90:91], s[0:1]
	v_cndmask_b32_e64 v4, 0, 1, s[0:1]
	v_cmp_ne_u32_e64 s[10:11], 1, v4
	s_andn2_b64 vcc, exec, s[0:1]
	s_cbranch_vccnz .LBB0_270
	v_lshlrev_b32_e32 v4, 5, v180
	v_and_b32_e32 v20, 0xf9e0, v4
	global_load_dwordx4 v[4:7], v20, s[62:63] offset:16
	global_load_dwordx4 v[16:19], v20, s[62:63]
	global_load_dwordx4 v[12:15], v20, s[82:83] offset:16
	s_nop 0
	global_load_dwordx4 v[20:23], v20, s[82:83]
.LBB0_270:
	s_ashr_i32 s7, s6, 31
	s_lshl_b64 s[0:1], s[6:7], 25
	s_add_u32 s0, s26, s0
	s_addc_u32 s1, s27, s1
	v_lshlrev_b32_e32 v152, 1, v184
	v_lshl_add_u64 v[184:185], s[0:1], 0, v[152:153]
	s_waitcnt vmcnt(0)
	s_cmp_lt_i32 s6, 7
	s_cselect_b64 s[50:51], -1, 0
	s_cmp_gt_u32 s6, 8
	s_cselect_b32 s58, 0x2000000, 0
	s_cmp_lt_u32 s14, 4
	s_mov_b64 s[0:1], -1
	v_mov_b32_e32 v190, v247
	s_cselect_b64 vcc, -1, 0
	v_lshlrev_b64 v[186:187], 11, v[180:181]
	v_cndmask_b32_e32 v152, 1.0, v213, vcc
	v_lshl_add_u64 v[188:189], v[184:185], 0, v[186:187]
	v_pk_mul_f32 v[192:193], v[142:143], v[190:191] op_sel_hi:[1,0]
	v_pk_mul_f32 v[194:195], v[140:141], v[190:191] op_sel_hi:[1,0]
	v_pk_mul_f32 v[140:141], v[138:139], v[190:191] op_sel_hi:[1,0]
	v_pk_mul_f32 v[142:143], v[136:137], v[190:191] op_sel_hi:[1,0]
	s_and_b64 vcc, exec, s[50:51]
	s_cbranch_vccz .LBB0_277
	s_and_b64 vcc, exec, s[16:17]
	s_cbranch_vccnz .LBB0_431
	s_and_b64 vcc, exec, s[0:1]
	s_cbranch_vccnz .LBB0_436

; template <int RSM> __device__ __forceinline__ float row_scale(const float* p, int row) { const float v = __hip_atomic_load(p + row, __ATOMIC_RELAXED, __HIP_MEMORY_SCOPE_AGENT); return RSM == 0 ? v : 1.0f / sqrtf(v * (1.f / DM) + EPS); }
;     __device__ __forceinline__ void operator()(const f32x4 (&acc)[2][2][4][2], const Unit& u, int wr, int wc, int fr, int fq) const {
;     ...
;             for (int m = 0; m < 4; ++m) { const int row = row0 + ai * HALF + m * 16; const float sc = row_scale<1>(rs, row);
;                 f32x4 c0, c1, s0, s1;
;                 if (rope) { const int pos = row & (SEQ - 1); c0 = *(const f32x4*)(ropeC + pos * 8); c1 = *(const f32x4*)(ropeC + pos * 8 + 4); s0 = *(const f32x4*)(ropeS + pos * 8); s1 = *(const f32x4*)(ropeS + pos * 8 + 4); }
; #pragma unroll
;                 for (int bj = 0; bj < 2; ++bj) { const f32x4 a0 = acc[ai][bj][m][0] * sc, a1 = acc[ai][bj][m][1] * sc;
.LBB0_288:
	v_or_b32_e32 v128, 16, v180
	v_ashrrev_i32_e32 v129, 31, v128
	v_lshl_add_u64 v[130:131], v[128:129], 2, s[88:89]
	s_nop 1
	s_and_b64 vcc, exec, s[10:11]
	s_cbranch_vccnz .LBB0_290
	v_lshlrev_b32_e32 v4, 5, v128
	v_and_b32_e32 v12, 0xfbe0, v4
	global_load_dwordx4 v[16:19], v12, s[62:63]
	global_load_dwordx4 v[4:7], v12, s[62:63] offset:16
	global_load_dwordx4 v[20:23], v12, s[82:83]
	s_nop 0
	global_load_dwordx4 v[12:15], v12, s[82:83] offset:16
.LBB0_290:
	s_waitcnt vmcnt(0)
	v_lshlrev_b64 v[128:129], 11, v[128:129]
	s_nop 0
	s_mov_b64 s[0:1], -1
	v_mov_b32_e32 v132, v248
	v_lshl_add_u64 v[130:131], v[184:185], 0, v[128:129]
	v_pk_mul_f32 v[134:135], v[126:127], v[132:133] op_sel_hi:[1,0]
	v_pk_mul_f32 v[136:137], v[124:125], v[132:133] op_sel_hi:[1,0]
	v_pk_mul_f32 v[124:125], v[122:123], v[132:133] op_sel_hi:[1,0]
	v_pk_mul_f32 v[126:127], v[120:121], v[132:133] op_sel_hi:[1,0]
	s_and_b64 vcc, exec, s[14:15]
	s_cbranch_vccnz .LBB0_297
	s_and_b64 vcc, exec, s[12:13]
	s_cbranch_vccz .LBB0_541
	s_and_b64 vcc, exec, s[0:1]
	s_cbranch_vccnz .LBB0_546

; template <int RSM> __device__ __forceinline__ float row_scale(const float* p, int row) { const float v = __hip_atomic_load(p + row, __ATOMIC_RELAXED, __HIP_MEMORY_SCOPE_AGENT); return RSM == 0 ? v : 1.0f / sqrtf(v * (1.f / DM) + EPS); }
;     __device__ __forceinline__ void operator()(const f32x4 (&acc)[2][2][4][2], const Unit& u, int wr, int wc, int fr, int fq) const {
;     ...
;             for (int m = 0; m < 4; ++m) { const int row = row0 + ai * HALF + m * 16; const float sc = row_scale<1>(rs, row);
;                 f32x4 c0, c1, s0, s1;
;                 if (rope) { const int pos = row & (SEQ - 1); c0 = *(const f32x4*)(ropeC + pos * 8); c1 = *(const f32x4*)(ropeC + pos * 8 + 4); s0 = *(const f32x4*)(ropeS + pos * 8); s1 = *(const f32x4*)(ropeS + pos * 8 + 4); }
; #pragma unroll
;                 for (int bj = 0; bj < 2; ++bj) { const f32x4 a0 = acc[ai][bj][m][0] * sc, a1 = acc[ai][bj][m][1] * sc;
.LBB0_308:
	v_or_b32_e32 v112, 32, v180
	v_ashrrev_i32_e32 v113, 31, v112
	v_lshl_add_u64 v[114:115], v[112:113], 2, s[88:89]
	s_nop 1
	s_and_b64 vcc, exec, s[10:11]
	s_cbranch_vccnz .LBB0_310
	v_lshlrev_b32_e32 v4, 5, v112
	v_and_b32_e32 v20, 0xfde0, v4
	global_load_dwordx4 v[4:7], v20, s[62:63] offset:16
	global_load_dwordx4 v[16:19], v20, s[62:63]
	global_load_dwordx4 v[12:15], v20, s[82:83] offset:16
	s_nop 0
	global_load_dwordx4 v[20:23], v20, s[82:83]
.LBB0_310:
	s_waitcnt vmcnt(0)
	v_lshlrev_b64 v[112:113], 11, v[112:113]
	s_nop 0
	s_mov_b64 s[0:1], -1
	v_mov_b32_e32 v116, v249
	v_lshl_add_u64 v[114:115], v[184:185], 0, v[112:113]
	v_pk_mul_f32 v[118:119], v[110:111], v[116:117] op_sel_hi:[1,0]
	v_pk_mul_f32 v[120:121], v[108:109], v[116:117] op_sel_hi:[1,0]
	v_pk_mul_f32 v[108:109], v[106:107], v[116:117] op_sel_hi:[1,0]
	v_pk_mul_f32 v[110:111], v[104:105], v[116:117] op_sel_hi:[1,0]
	s_and_b64 vcc, exec, s[14:15]
	s_cbranch_vccnz .LBB0_317
	s_and_b64 vcc, exec, s[12:13]
	s_cbranch_vccz .LBB0_651
	s_and_b64 vcc, exec, s[0:1]
	s_cbranch_vccnz .LBB0_656

; template <int RSM> __device__ __forceinline__ float row_scale(const float* p, int row) { const float v = __hip_atomic_load(p + row, __ATOMIC_RELAXED, __HIP_MEMORY_SCOPE_AGENT); return RSM == 0 ? v : 1.0f / sqrtf(v * (1.f / DM) + EPS); }
;     __device__ __forceinline__ void operator()(const f32x4 (&acc)[2][2][4][2], const Unit& u, int wr, int wc, int fr, int fq) const {
;     ...
;             for (int m = 0; m < 4; ++m) { const int row = row0 + ai * HALF + m * 16; const float sc = row_scale<1>(rs, row);
;                 f32x4 c0, c1, s0, s1;
;                 if (rope) { const int pos = row & (SEQ - 1); c0 = *(const f32x4*)(ropeC + pos * 8); c1 = *(const f32x4*)(ropeC + pos * 8 + 4); s0 = *(const f32x4*)(ropeS + pos * 8); s1 = *(const f32x4*)(ropeS + pos * 8 + 4); }
; #pragma unroll
;                 for (int bj = 0; bj < 2; ++bj) { const f32x4 a0 = acc[ai][bj][m][0] * sc, a1 = acc[ai][bj][m][1] * sc;
.LBB0_328:
	v_or_b32_e32 v96, 48, v180
	v_ashrrev_i32_e32 v97, 31, v96
	v_lshl_add_u64 v[98:99], v[96:97], 2, s[88:89]
	s_nop 1
	s_and_b64 vcc, exec, s[10:11]
	s_cbranch_vccnz .LBB0_330
	v_lshlrev_b32_e32 v4, 5, v96
	v_and_b32_e32 v20, 0xffe0, v4
	global_load_dwordx4 v[4:7], v20, s[62:63] offset:16
	global_load_dwordx4 v[16:19], v20, s[62:63]
	global_load_dwordx4 v[12:15], v20, s[82:83] offset:16
	s_nop 0
	global_load_dwordx4 v[20:23], v20, s[82:83]
.LBB0_330:
	s_waitcnt vmcnt(0)
	v_lshlrev_b64 v[96:97], 11, v[96:97]
	s_nop 0
	s_mov_b64 s[0:1], -1
	v_mov_b32_e32 v100, v251
	v_lshl_add_u64 v[98:99], v[184:185], 0, v[96:97]
	v_pk_mul_f32 v[102:103], v[94:95], v[100:101] op_sel_hi:[1,0]
	v_pk_mul_f32 v[104:105], v[92:93], v[100:101] op_sel_hi:[1,0]
	v_pk_mul_f32 v[92:93], v[90:91], v[100:101] op_sel_hi:[1,0]
	v_pk_mul_f32 v[94:95], v[88:89], v[100:101] op_sel_hi:[1,0]
	s_and_b64 vcc, exec, s[14:15]
	s_cbranch_vccnz .LBB0_337
	s_and_b64 vcc, exec, s[12:13]
	s_cbranch_vccz .LBB0_761
	s_and_b64 vcc, exec, s[0:1]
	s_cbranch_vccnz .LBB0_766

; template <int RSM> __device__ __forceinline__ float row_scale(const float* p, int row) { const float v = __hip_atomic_load(p + row, __ATOMIC_RELAXED, __HIP_MEMORY_SCOPE_AGENT); return RSM == 0 ? v : 1.0f / sqrtf(v * (1.f / DM) + EPS); }
;     __device__ __forceinline__ void operator()(const f32x4 (&acc)[2][2][4][2], const Unit& u, int wr, int wc, int fr, int fq) const {
;     ...
;             for (int m = 0; m < 4; ++m) { const int row = row0 + ai * HALF + m * 16; const float sc = row_scale<1>(rs, row);
;                 f32x4 c0, c1, s0, s1;
;                 if (rope) { const int pos = row & (SEQ - 1); c0 = *(const f32x4*)(ropeC + pos * 8); c1 = *(const f32x4*)(ropeC + pos * 8 + 4); s0 = *(const f32x4*)(ropeS + pos * 8); s1 = *(const f32x4*)(ropeS + pos * 8 + 4); }
; #pragma unroll
;                 for (int bj = 0; bj < 2; ++bj) { const f32x4 a0 = acc[ai][bj][m][0] * sc, a1 = acc[ai][bj][m][1] * sc;
.LBB0_348:
	s_nop 1
	v_add_u32_e32 v80, 0x80, v180
	s_and_b64 vcc, exec, s[10:11]
	v_ashrrev_i32_e32 v81, 31, v80
	s_cbranch_vccnz .LBB0_350
	v_lshlrev_b32_e32 v4, 5, v80
	v_and_b32_e32 v20, 0xf9e0, v4
	global_load_dwordx4 v[4:7], v20, s[62:63] offset:16
	global_load_dwordx4 v[16:19], v20, s[62:63]
	global_load_dwordx4 v[12:15], v20, s[82:83] offset:16
	s_nop 0
	global_load_dwordx4 v[20:23], v20, s[82:83]
.LBB0_350:
	s_waitcnt vmcnt(0)
	v_lshlrev_b64 v[80:81], 11, v[80:81]
	s_nop 0
	s_mov_b64 s[0:1], -1
	v_mov_b32_e32 v84, v252
	v_lshl_add_u64 v[82:83], v[184:185], 0, v[80:81]
	v_pk_mul_f32 v[86:87], v[78:79], v[84:85] op_sel_hi:[1,0]
	v_pk_mul_f32 v[88:89], v[76:77], v[84:85] op_sel_hi:[1,0]
	v_pk_mul_f32 v[76:77], v[74:75], v[84:85] op_sel_hi:[1,0]
	v_pk_mul_f32 v[78:79], v[72:73], v[84:85] op_sel_hi:[1,0]
	s_and_b64 vcc, exec, s[14:15]
	s_cbranch_vccnz .LBB0_357
	s_and_b64 vcc, exec, s[12:13]
	s_cbranch_vccz .LBB0_871
	s_and_b64 vcc, exec, s[0:1]
	s_cbranch_vccnz .LBB0_876

; template <int RSM> __device__ __forceinline__ float row_scale(const float* p, int row) { const float v = __hip_atomic_load(p + row, __ATOMIC_RELAXED, __HIP_MEMORY_SCOPE_AGENT); return RSM == 0 ? v : 1.0f / sqrtf(v * (1.f / DM) + EPS); }
;     __device__ __forceinline__ void operator()(const f32x4 (&acc)[2][2][4][2], const Unit& u, int wr, int wc, int fr, int fq) const {
;     ...
;             for (int m = 0; m < 4; ++m) { const int row = row0 + ai * HALF + m * 16; const float sc = row_scale<1>(rs, row);
;                 f32x4 c0, c1, s0, s1;
;                 if (rope) { const int pos = row & (SEQ - 1); c0 = *(const f32x4*)(ropeC + pos * 8); c1 = *(const f32x4*)(ropeC + pos * 8 + 4); s0 = *(const f32x4*)(ropeS + pos * 8); s1 = *(const f32x4*)(ropeS + pos * 8 + 4); }
; #pragma unroll
;                 for (int bj = 0; bj < 2; ++bj) { const f32x4 a0 = acc[ai][bj][m][0] * sc, a1 = acc[ai][bj][m][1] * sc;
.LBB0_368:
	s_nop 1
	v_add_u32_e32 v64, 0x90, v180
	s_and_b64 vcc, exec, s[10:11]
	v_ashrrev_i32_e32 v65, 31, v64
	s_cbranch_vccnz .LBB0_370
	v_lshlrev_b32_e32 v4, 5, v64
	v_and_b32_e32 v20, 0xfbe0, v4
	global_load_dwordx4 v[4:7], v20, s[62:63] offset:16
	global_load_dwordx4 v[16:19], v20, s[62:63]
	global_load_dwordx4 v[12:15], v20, s[82:83] offset:16
	s_nop 0
	global_load_dwordx4 v[20:23], v20, s[82:83]
.LBB0_370:
	s_waitcnt vmcnt(0)
	v_lshlrev_b64 v[64:65], 11, v[64:65]
	s_nop 0
	s_mov_b64 s[0:1], -1
	v_mov_b32_e32 v68, v253
	v_lshl_add_u64 v[66:67], v[184:185], 0, v[64:65]
	v_pk_mul_f32 v[70:71], v[62:63], v[68:69] op_sel_hi:[1,0]
	v_pk_mul_f32 v[72:73], v[60:61], v[68:69] op_sel_hi:[1,0]
	v_pk_mul_f32 v[60:61], v[58:59], v[68:69] op_sel_hi:[1,0]
	v_pk_mul_f32 v[62:63], v[56:57], v[68:69] op_sel_hi:[1,0]
	s_and_b64 vcc, exec, s[14:15]
	s_cbranch_vccnz .LBB0_377
	s_and_b64 vcc, exec, s[12:13]
	s_cbranch_vccz .LBB0_981
	s_and_b64 vcc, exec, s[0:1]
	s_cbranch_vccnz .LBB0_986

; template <int RSM> __device__ __forceinline__ float row_scale(const float* p, int row) { const float v = __hip_atomic_load(p + row, __ATOMIC_RELAXED, __HIP_MEMORY_SCOPE_AGENT); return RSM == 0 ? v : 1.0f / sqrtf(v * (1.f / DM) + EPS); }
;     __device__ __forceinline__ void operator()(const f32x4 (&acc)[2][2][4][2], const Unit& u, int wr, int wc, int fr, int fq) const {
;     ...
;             for (int m = 0; m < 4; ++m) { const int row = row0 + ai * HALF + m * 16; const float sc = row_scale<1>(rs, row);
;                 f32x4 c0, c1, s0, s1;
;                 if (rope) { const int pos = row & (SEQ - 1); c0 = *(const f32x4*)(ropeC + pos * 8); c1 = *(const f32x4*)(ropeC + pos * 8 + 4); s0 = *(const f32x4*)(ropeS + pos * 8); s1 = *(const f32x4*)(ropeS + pos * 8 + 4); }
; #pragma unroll
;                 for (int bj = 0; bj < 2; ++bj) { const f32x4 a0 = acc[ai][bj][m][0] * sc, a1 = acc[ai][bj][m][1] * sc;
.LBB0_388:
	s_nop 1
	v_add_u32_e32 v48, 0xa0, v180
	s_and_b64 vcc, exec, s[10:11]
	v_ashrrev_i32_e32 v49, 31, v48
	s_cbranch_vccnz .LBB0_390
	v_lshlrev_b32_e32 v4, 5, v48
	v_and_b32_e32 v20, 0xfde0, v4
	global_load_dwordx4 v[4:7], v20, s[62:63] offset:16
	global_load_dwordx4 v[16:19], v20, s[62:63]
	global_load_dwordx4 v[12:15], v20, s[82:83] offset:16
	s_nop 0
	global_load_dwordx4 v[20:23], v20, s[82:83]
.LBB0_390:
	s_waitcnt vmcnt(0)
	v_lshlrev_b64 v[48:49], 11, v[48:49]
	s_nop 0
	s_mov_b64 s[0:1], -1
	v_mov_b32_e32 v52, v254
	v_lshl_add_u64 v[50:51], v[184:185], 0, v[48:49]
	v_pk_mul_f32 v[54:55], v[46:47], v[52:53] op_sel_hi:[1,0]
	v_pk_mul_f32 v[56:57], v[44:45], v[52:53] op_sel_hi:[1,0]
	v_pk_mul_f32 v[44:45], v[42:43], v[52:53] op_sel_hi:[1,0]
	v_pk_mul_f32 v[46:47], v[40:41], v[52:53] op_sel_hi:[1,0]
	s_and_b64 vcc, exec, s[14:15]
	s_cbranch_vccnz .LBB0_397
	s_and_b64 vcc, exec, s[12:13]
	s_cbranch_vccz .LBB0_1091
	s_and_b64 vcc, exec, s[0:1]
	s_cbranch_vccnz .LBB0_1096

; template <int RSM> __device__ __forceinline__ float row_scale(const float* p, int row) { const float v = __hip_atomic_load(p + row, __ATOMIC_RELAXED, __HIP_MEMORY_SCOPE_AGENT); return RSM == 0 ? v : 1.0f / sqrtf(v * (1.f / DM) + EPS); }
;     __device__ __forceinline__ void operator()(const f32x4 (&acc)[2][2][4][2], const Unit& u, int wr, int wc, int fr, int fq) const {
;     ...
;             for (int m = 0; m < 4; ++m) { const int row = row0 + ai * HALF + m * 16; const float sc = row_scale<1>(rs, row);
;                 f32x4 c0, c1, s0, s1;
;                 if (rope) { const int pos = row & (SEQ - 1); c0 = *(const f32x4*)(ropeC + pos * 8); c1 = *(const f32x4*)(ropeC + pos * 8 + 4); s0 = *(const f32x4*)(ropeS + pos * 8); s1 = *(const f32x4*)(ropeS + pos * 8 + 4); }
; #pragma unroll
;                 for (int bj = 0; bj < 2; ++bj) { const f32x4 a0 = acc[ai][bj][m][0] * sc, a1 = acc[ai][bj][m][1] * sc;
.LBB0_408:
	s_nop 1
	v_add_u32_e32 v32, 0xb0, v180
	s_and_b64 vcc, exec, s[10:11]
	v_ashrrev_i32_e32 v33, 31, v32
	s_cbranch_vccnz .LBB0_410
	v_lshlrev_b32_e32 v4, 5, v32
	v_and_b32_e32 v20, 0xffe0, v4
	global_load_dwordx4 v[4:7], v20, s[62:63] offset:16
	global_load_dwordx4 v[16:19], v20, s[62:63]
	global_load_dwordx4 v[12:15], v20, s[82:83] offset:16
	s_nop 0
	global_load_dwordx4 v[20:23], v20, s[82:83]
.LBB0_410:
	s_waitcnt vmcnt(0)
	v_lshlrev_b64 v[32:33], 11, v[32:33]
	s_nop 0
	s_mov_b64 s[0:1], -1
	v_mov_b32_e32 v36, v255
	v_lshl_add_u64 v[34:35], v[184:185], 0, v[32:33]
	v_pk_mul_f32 v[38:39], v[30:31], v[36:37] op_sel_hi:[1,0]
	v_pk_mul_f32 v[40:41], v[28:29], v[36:37] op_sel_hi:[1,0]
	v_pk_mul_f32 v[28:29], v[26:27], v[36:37] op_sel_hi:[1,0]
	v_pk_mul_f32 v[30:31], v[24:25], v[36:37] op_sel_hi:[1,0]
	s_and_b64 vcc, exec, s[14:15]
	s_cbranch_vccnz .LBB0_417
	s_and_b64 vcc, exec, s[12:13]
	s_cbranch_vccz .LBB0_1201
	s_and_b64 vcc, exec, s[0:1]
	s_cbranch_vccnz .LBB0_1206

; __device__ __forceinline__ float silu(float x) { return x * sigm(x); }
; __device__ __forceinline__ unsigned pkbf(float lo, float hi) { const f32x2_m v = {lo, hi}; const bf16x2_m b = __builtin_convertvector(v, bf16x2_m); return __builtin_bit_cast(unsigned, b); }
; template <int RSM> __device__ __forceinline__ float row_scale(const float* p, int row) { const float v = __hip_atomic_load(p + row, __ATOMIC_RELAXED, __HIP_MEMORY_SCOPE_AGENT); return RSM == 0 ? v : 1.0f / sqrtf(v * (1.f / DM) + EPS); }
;     __device__ __forceinline__ void operator()(const f32x4 (&acc)[2][2][4][2], const Unit& u, int wr, int wc, int fr, int fq) const {
;     ...
;             for (int m = 0; m < 4; ++m) { const int row = row0 + ai * HALF + m * 16; bf16* rowp = O + (size_t)row * ldc + col0; const float sc = row_scale<RSM>(rs, row);
;                 const f32x4 g0 = acc[ai][0][m][0] * sc, g1 = acc[ai][0][m][1] * sc, u0 = acc[ai][1][m][0] * sc, u1 = acc[ai][1][m][1] * sc;
;                 v4u w; w.x = pkbf(silu(g0[0]) * u0[0], silu(g0[1]) * u0[1]); w.y = pkbf(silu(g0[2]) * u0[2], silu(g0[3]) * u0[3]);
;                 w.z = pkbf(silu(g1[0]) * u1[0], silu(g1[1]) * u1[1]); w.w = pkbf(silu(g1[2]) * u1[2], silu(g1[3]) * u1[3]);
;                 *(v4u*)rowp = w; }
.LBB0_1885:
	v_lshl_add_u32 v144, s6, 8, v152
	v_ashrrev_i32_e32 v145, 31, v144
	v_lshl_add_u64 v[150:151], v[144:145], 2, s[12:13]
	global_load_dword v245, v[150:151], off sc1
	global_load_dword v246, v[150:151], off offset:64 sc1
	global_load_dword v247, v[150:151], off offset:128 sc1
	global_load_dword v248, v[150:151], off offset:192 sc1
	global_load_dword v249, v[150:151], off offset:512 sc1
	global_load_dword v251, v[150:151], off offset:576 sc1
	global_load_dword v252, v[150:151], off offset:640 sc1
	global_load_dword v253, v[150:151], off offset:704 sc1
	v_bfe_u32 v163, v222, 4, 1
	v_cmp_ne_u32_e64 s[98:99], 0, v163
	v_bfe_u32 v163, v222, 5, 1
	v_cmp_ne_u32_e64 s[100:101], 0, v163
	v_and_b32_e32 v145, 15, v222
	v_lshlrev_b32_e32 v145, 2, v145
	s_waitcnt vmcnt(0)
	v_cndmask_b32_e64 v245, v245, v247, s[98:99]
	v_cndmask_b32_e64 v249, v249, v252, s[98:99]
	v_cndmask_b32_e64 v245, v245, v249, s[100:101]
	v_cndmask_b32_e64 v246, v246, v248, s[98:99]
	v_cndmask_b32_e64 v251, v251, v253, s[98:99]
	v_cndmask_b32_e64 v246, v246, v251, s[100:101]
	v_fmamk_f32 v245, v245, 0x3a000000, v158
	v_mul_f32_e32 v163, 0x4f800000, v245
	v_cmp_gt_f32_e32 vcc, s50, v245
	s_nop 1
	v_cndmask_b32_e32 v245, v245, v163, vcc
	v_sqrt_f32_e32 v164, v245
	s_nop 0
	v_add_u32_e32 v165, -1, v164
	v_add_u32_e32 v166, 1, v164
	v_fma_f32 v167, -v165, v164, v245
	v_fma_f32 v168, -v166, v164, v245
	v_cmp_ge_f32_e64 s[98:99], 0, v167
	s_nop 1
	v_cndmask_b32_e64 v164, v164, v165, s[98:99]
	v_cmp_lt_f32_e64 s[98:99], 0, v168
	s_nop 1
	v_cndmask_b32_e64 v164, v164, v166, s[98:99]
	v_mul_f32_e32 v165, 0x37800000, v164
	v_cndmask_b32_e32 v164, v164, v165, vcc
	v_cmp_class_f32_e32 vcc, v245, v159
	s_nop 1
	v_cndmask_b32_e32 v245, v164, v245, vcc
	v_div_scale_f32 v166, s[100:101], v245, v245, 1.0
	v_rcp_f32_e32 v167, v166
	v_div_scale_f32 v163, vcc, 1.0, v245, 1.0
	v_fma_f32 v168, -v166, v167, 1.0
	v_fmac_f32_e32 v167, v168, v167
	v_mul_f32_e32 v168, v163, v167
	v_fma_f32 v169, -v166, v168, v163
	v_fmac_f32_e32 v168, v169, v167
	v_fma_f32 v163, -v166, v168, v163
	v_div_fmas_f32 v163, v163, v167, v168
	v_div_fixup_f32 v245, v163, v245, 1.0
	v_fmamk_f32 v246, v246, 0x3a000000, v158
	v_mul_f32_e32 v163, 0x4f800000, v246
	v_cmp_gt_f32_e32 vcc, s50, v246
	s_nop 1
	v_cndmask_b32_e32 v246, v246, v163, vcc
	v_sqrt_f32_e32 v164, v246
	s_nop 0
	v_add_u32_e32 v165, -1, v164
	v_add_u32_e32 v166, 1, v164
	v_fma_f32 v167, -v165, v164, v246
	v_fma_f32 v168, -v166, v164, v246
	v_cmp_ge_f32_e64 s[98:99], 0, v167
	s_nop 1
	v_cndmask_b32_e64 v164, v164, v165, s[98:99]
	v_cmp_lt_f32_e64 s[98:99], 0, v168
	s_nop 1
	v_cndmask_b32_e64 v164, v164, v166, s[98:99]
	v_mul_f32_e32 v165, 0x37800000, v164
	v_cndmask_b32_e32 v164, v164, v165, vcc
	v_cmp_class_f32_e32 vcc, v246, v159
	s_nop 1
	v_cndmask_b32_e32 v246, v164, v246, vcc
	v_div_scale_f32 v166, s[100:101], v246, v246, 1.0
	v_rcp_f32_e32 v167, v166
	v_div_scale_f32 v163, vcc, 1.0, v246, 1.0
	v_fma_f32 v168, -v166, v167, 1.0
	v_fmac_f32_e32 v167, v168, v167
	v_mul_f32_e32 v168, v163, v167
	v_fma_f32 v169, -v166, v168, v163
	v_fmac_f32_e32 v168, v169, v167
	v_fma_f32 v163, -v166, v168, v163
	v_div_fmas_f32 v163, v163, v167, v168
	v_div_fixup_f32 v246, v163, v246, 1.0
	ds_bpermute_b32 v247, v145, v245
	ds_bpermute_b32 v248, v145, v246
	ds_bpermute_b32 v249, v145, v245 offset:64
	ds_bpermute_b32 v251, v145, v246 offset:64
	ds_bpermute_b32 v252, v145, v245 offset:128
	ds_bpermute_b32 v253, v145, v246 offset:128
	ds_bpermute_b32 v254, v145, v245 offset:192
	ds_bpermute_b32 v255, v145, v246 offset:192
	s_waitcnt lgkmcnt(0)
	v_lshl_or_b32 v148, s7, 7, v154
	v_or_b32_e32 v162, 16, v144
	v_mov_b64_e32 v[146:147], s[26:27]
	v_ashrrev_i32_e32 v149, 31, v148
	v_mad_i64_i32 v[160:161], s[0:1], v144, s47, v[146:147]
	v_lshlrev_b64 v[148:149], 1, v[148:149]
	v_lshl_add_u64 v[160:161], v[160:161], 0, v[148:149]
	v_ashrrev_i32_e32 v163, 31, v162
	v_lshl_add_u64 v[164:165], v[162:163], 2, s[12:13]
	v_mov_b32_e32 v166, v247
	v_pk_mul_f32 v[126:127], v[126:127], v[166:167] op_sel_hi:[1,0]
	v_pk_mul_f32 v[124:125], v[124:125], v[166:167] op_sel_hi:[1,0]
	v_pk_mul_f32 v[122:123], v[122:123], v[166:167] op_sel_hi:[1,0]
	v_pk_mul_f32 v[120:121], v[120:121], v[166:167] op_sel_hi:[1,0]
	v_pk_mul_f32 v[118:119], v[118:119], v[166:167] op_sel_hi:[1,0]
	v_pk_mul_f32 v[116:117], v[116:117], v[166:167] op_sel_hi:[1,0]
	v_pk_mul_f32 v[114:115], v[114:115], v[166:167] op_sel_hi:[1,0]
	v_pk_mul_f32 v[112:113], v[112:113], v[166:167] op_sel_hi:[1,0]
	v_mul_f32_e32 v145, 0xbfb8aa3b, v124
	v_mul_f32_e32 v163, 0xbfb8aa3b, v125
	v_mul_f32_e32 v166, 0xbfb8aa3b, v126
	v_mul_f32_e32 v167, 0xbfb8aa3b, v127
	v_mul_f32_e32 v168, 0xbfb8aa3b, v120
	v_mul_f32_e32 v169, 0xbfb8aa3b, v121
	v_mul_f32_e32 v170, 0xbfb8aa3b, v122
	v_mul_f32_e32 v171, 0xbfb8aa3b, v123
	v_exp_f32_e32 v145, v145
	v_exp_f32_e32 v163, v163
	v_exp_f32_e32 v166, v166
	v_exp_f32_e32 v167, v167
	v_exp_f32_e32 v168, v168
	v_exp_f32_e32 v169, v169
	v_exp_f32_e32 v170, v170
	v_exp_f32_e32 v171, v171
	v_add_f32_e32 v145, 1.0, v145
	v_add_f32_e32 v163, 1.0, v163
	v_add_f32_e32 v172, 1.0, v166
	v_add_f32_e32 v173, 1.0, v167
	v_add_f32_e32 v174, 1.0, v168
	v_add_f32_e32 v175, 1.0, v169
	v_add_f32_e32 v176, 1.0, v170
	v_add_f32_e32 v177, 1.0, v171
	v_rcp_f32_e32 v166, v145
	v_rcp_f32_e32 v167, v163
	v_rcp_f32_e32 v168, v172
	v_rcp_f32_e32 v169, v173
	v_rcp_f32_e32 v170, v174
	v_rcp_f32_e32 v171, v175
	v_rcp_f32_e32 v172, v176
	v_rcp_f32_e32 v173, v177
	v_pk_mul_f32 v[124:125], v[124:125], v[166:167]
	v_pk_mul_f32 v[126:127], v[126:127], v[168:169]
	v_pk_mul_f32 v[120:121], v[120:121], v[170:171]
	v_pk_mul_f32 v[122:123], v[122:123], v[172:173]
; __device__ __forceinline__ float silu(float x) { return x * sigm(x); }
; __device__ __forceinline__ unsigned pkbf(float lo, float hi) { const f32x2_m v = {lo, hi}; const bf16x2_m b = __builtin_convertvector(v, bf16x2_m); return __builtin_bit_cast(unsigned, b); }
; template <int RSM> __device__ __forceinline__ float row_scale(const float* p, int row) { const float v = __hip_atomic_load(p + row, __ATOMIC_RELAXED, __HIP_MEMORY_SCOPE_AGENT); return RSM == 0 ? v : 1.0f / sqrtf(v * (1.f / DM) + EPS); }
;     __device__ __forceinline__ void operator()(const f32x4 (&acc)[2][2][4][2], const Unit& u, int wr, int wc, int fr, int fq) const {
;     ...
;             for (int m = 0; m < 4; ++m) { const int row = row0 + ai * HALF + m * 16; bf16* rowp = O + (size_t)row * ldc + col0; const float sc = row_scale<RSM>(rs, row);
;                 const f32x4 g0 = acc[ai][0][m][0] * sc, g1 = acc[ai][0][m][1] * sc, u0 = acc[ai][1][m][0] * sc, u1 = acc[ai][1][m][1] * sc;
;                 v4u w; w.x = pkbf(silu(g0[0]) * u0[0], silu(g0[1]) * u0[1]); w.y = pkbf(silu(g0[2]) * u0[2], silu(g0[3]) * u0[3]);
;                 w.z = pkbf(silu(g1[0]) * u1[0], silu(g1[1]) * u1[1]); w.w = pkbf(silu(g1[2]) * u1[2], silu(g1[3]) * u1[3]);
;                 *(v4u*)rowp = w; }
	v_pk_mul_f32 v[116:117], v[116:117], v[124:125]
	v_pk_mul_f32 v[118:119], v[118:119], v[126:127]
	v_pk_mul_f32 v[120:121], v[112:113], v[120:121]
	v_pk_mul_f32 v[122:123], v[114:115], v[122:123]
	v_cvt_pk_bf16_f32 v112, v116, v117
	v_cvt_pk_bf16_f32 v113, v118, v119
	v_cvt_pk_bf16_f32 v114, v120, v121
	v_cvt_pk_bf16_f32 v115, v122, v123
	global_store_dwordx4 v[160:161], v[112:115], off
	s_nop 1
	v_or_b32_e32 v112, 32, v144
	v_ashrrev_i32_e32 v113, 31, v112
	v_mad_i64_i32 v[114:115], s[0:1], v162, s47, v[146:147]
	v_lshl_add_u64 v[114:115], v[114:115], 0, v[148:149]
	s_nop 0
	v_lshl_add_u64 v[116:117], v[112:113], 2, s[12:13]
	v_mov_b32_e32 v118, v248
	v_pk_mul_f32 v[110:111], v[110:111], v[118:119] op_sel_hi:[1,0]
	v_pk_mul_f32 v[108:109], v[108:109], v[118:119] op_sel_hi:[1,0]
	v_pk_mul_f32 v[106:107], v[106:107], v[118:119] op_sel_hi:[1,0]
	v_pk_mul_f32 v[104:105], v[104:105], v[118:119] op_sel_hi:[1,0]
	v_pk_mul_f32 v[102:103], v[102:103], v[118:119] op_sel_hi:[1,0]
	v_pk_mul_f32 v[100:101], v[100:101], v[118:119] op_sel_hi:[1,0]
	v_pk_mul_f32 v[98:99], v[98:99], v[118:119] op_sel_hi:[1,0]
	v_pk_mul_f32 v[96:97], v[96:97], v[118:119] op_sel_hi:[1,0]
	v_mul_f32_e32 v113, 0xbfb8aa3b, v108
	v_mul_f32_e32 v118, 0xbfb8aa3b, v109
	v_mul_f32_e32 v119, 0xbfb8aa3b, v110
	v_mul_f32_e32 v120, 0xbfb8aa3b, v111
	v_mul_f32_e32 v121, 0xbfb8aa3b, v104
	v_mul_f32_e32 v122, 0xbfb8aa3b, v105
	v_mul_f32_e32 v123, 0xbfb8aa3b, v106
	v_mul_f32_e32 v124, 0xbfb8aa3b, v107
	v_exp_f32_e32 v113, v113
	v_exp_f32_e32 v118, v118
	v_exp_f32_e32 v119, v119
	v_exp_f32_e32 v120, v120
	v_exp_f32_e32 v121, v121
	v_exp_f32_e32 v122, v122
	v_exp_f32_e32 v123, v123
	v_exp_f32_e32 v124, v124
	v_add_f32_e32 v113, 1.0, v113
	v_add_f32_e32 v125, 1.0, v118
	v_add_f32_e32 v126, 1.0, v119
	v_add_f32_e32 v127, 1.0, v120
	v_add_f32_e32 v145, 1.0, v121
	v_add_f32_e32 v160, 1.0, v122
	v_add_f32_e32 v161, 1.0, v123
	v_add_f32_e32 v162, 1.0, v124
	v_rcp_f32_e32 v118, v113
	v_rcp_f32_e32 v119, v125
	v_rcp_f32_e32 v120, v126
	v_rcp_f32_e32 v121, v127
	v_rcp_f32_e32 v122, v145
	v_rcp_f32_e32 v123, v160
	v_rcp_f32_e32 v124, v161
	v_rcp_f32_e32 v125, v162
	v_pk_mul_f32 v[108:109], v[108:109], v[118:119]
	v_pk_mul_f32 v[110:111], v[110:111], v[120:121]
	v_pk_mul_f32 v[104:105], v[104:105], v[122:123]
	v_pk_mul_f32 v[106:107], v[106:107], v[124:125]
	v_pk_mul_f32 v[100:101], v[100:101], v[108:109]
	v_pk_mul_f32 v[102:103], v[102:103], v[110:111]
	v_pk_mul_f32 v[104:105], v[96:97], v[104:105]
	v_pk_mul_f32 v[106:107], v[98:99], v[106:107]
	v_cvt_pk_bf16_f32 v96, v100, v101
	v_cvt_pk_bf16_f32 v97, v102, v103
	v_cvt_pk_bf16_f32 v98, v104, v105
	v_cvt_pk_bf16_f32 v99, v106, v107
	global_store_dwordx4 v[114:115], v[96:99], off
	s_nop 1
	v_or_b32_e32 v96, 48, v144
	v_ashrrev_i32_e32 v97, 31, v96
	v_mad_i64_i32 v[98:99], s[0:1], v112, s47, v[146:147]
	v_lshl_add_u64 v[98:99], v[98:99], 0, v[148:149]
	s_nop 0
	v_lshl_add_u64 v[100:101], v[96:97], 2, s[12:13]
	v_mov_b32_e32 v102, v249
	v_pk_mul_f32 v[94:95], v[94:95], v[102:103] op_sel_hi:[1,0]
	v_pk_mul_f32 v[92:93], v[92:93], v[102:103] op_sel_hi:[1,0]
	v_pk_mul_f32 v[90:91], v[90:91], v[102:103] op_sel_hi:[1,0]
	v_pk_mul_f32 v[88:89], v[88:89], v[102:103] op_sel_hi:[1,0]
	v_pk_mul_f32 v[86:87], v[86:87], v[102:103] op_sel_hi:[1,0]
	v_pk_mul_f32 v[84:85], v[84:85], v[102:103] op_sel_hi:[1,0]
	v_pk_mul_f32 v[82:83], v[82:83], v[102:103] op_sel_hi:[1,0]
	v_pk_mul_f32 v[80:81], v[80:81], v[102:103] op_sel_hi:[1,0]
	v_mul_f32_e32 v97, 0xbfb8aa3b, v92
	v_mul_f32_e32 v102, 0xbfb8aa3b, v93
	v_mul_f32_e32 v103, 0xbfb8aa3b, v94
	v_mul_f32_e32 v104, 0xbfb8aa3b, v95
	v_mul_f32_e32 v105, 0xbfb8aa3b, v88
	v_mul_f32_e32 v106, 0xbfb8aa3b, v89
	v_mul_f32_e32 v107, 0xbfb8aa3b, v90
	v_mul_f32_e32 v108, 0xbfb8aa3b, v91
	v_exp_f32_e32 v97, v97
	v_exp_f32_e32 v102, v102
	v_exp_f32_e32 v103, v103
	v_exp_f32_e32 v104, v104
	v_exp_f32_e32 v105, v105
	v_exp_f32_e32 v106, v106
	v_exp_f32_e32 v107, v107
	v_exp_f32_e32 v108, v108
	v_add_f32_e32 v97, 1.0, v97
	v_add_f32_e32 v109, 1.0, v102
	v_add_f32_e32 v110, 1.0, v103
	v_add_f32_e32 v111, 1.0, v104
	v_add_f32_e32 v112, 1.0, v105
	v_add_f32_e32 v113, 1.0, v106
	v_add_f32_e32 v114, 1.0, v107
	v_add_f32_e32 v115, 1.0, v108
	v_rcp_f32_e32 v102, v97
	v_rcp_f32_e32 v103, v109
	v_rcp_f32_e32 v104, v110
	v_rcp_f32_e32 v105, v111
	v_rcp_f32_e32 v106, v112
	v_rcp_f32_e32 v107, v113
	v_rcp_f32_e32 v108, v114
	v_rcp_f32_e32 v109, v115
	v_pk_mul_f32 v[92:93], v[92:93], v[102:103]
	v_pk_mul_f32 v[94:95], v[94:95], v[104:105]
	v_pk_mul_f32 v[88:89], v[88:89], v[106:107]
	v_pk_mul_f32 v[90:91], v[90:91], v[108:109]
	v_pk_mul_f32 v[84:85], v[84:85], v[92:93]
	v_pk_mul_f32 v[86:87], v[86:87], v[94:95]
	v_pk_mul_f32 v[88:89], v[80:81], v[88:89]
	v_pk_mul_f32 v[90:91], v[82:83], v[90:91]
	v_cvt_pk_bf16_f32 v80, v84, v85
	v_cvt_pk_bf16_f32 v81, v86, v87
	v_cvt_pk_bf16_f32 v82, v88, v89
	v_cvt_pk_bf16_f32 v83, v90, v91
	global_store_dwordx4 v[98:99], v[80:83], off
	s_nop 1
	v_mad_i64_i32 v[80:81], s[0:1], v96, s47, v[146:147]
	v_lshl_add_u64 v[80:81], v[80:81], 0, v[148:149]
	v_mov_b32_e32 v82, v251
	v_pk_mul_f32 v[78:79], v[78:79], v[82:83] op_sel_hi:[1,0]
	v_pk_mul_f32 v[76:77], v[76:77], v[82:83] op_sel_hi:[1,0]
	v_pk_mul_f32 v[74:75], v[74:75], v[82:83] op_sel_hi:[1,0]
	v_pk_mul_f32 v[72:73], v[72:73], v[82:83] op_sel_hi:[1,0]
	v_pk_mul_f32 v[70:71], v[70:71], v[82:83] op_sel_hi:[1,0]
	v_pk_mul_f32 v[68:69], v[68:69], v[82:83] op_sel_hi:[1,0]
	v_pk_mul_f32 v[66:67], v[66:67], v[82:83] op_sel_hi:[1,0]
	v_pk_mul_f32 v[64:65], v[64:65], v[82:83] op_sel_hi:[1,0]
	v_mul_f32_e32 v82, 0xbfb8aa3b, v76
	v_mul_f32_e32 v83, 0xbfb8aa3b, v77
; __device__ __forceinline__ float silu(float x) { return x * sigm(x); }
; __device__ __forceinline__ unsigned pkbf(float lo, float hi) { const f32x2_m v = {lo, hi}; const bf16x2_m b = __builtin_convertvector(v, bf16x2_m); return __builtin_bit_cast(unsigned, b); }
; template <int RSM> __device__ __forceinline__ float row_scale(const float* p, int row) { const float v = __hip_atomic_load(p + row, __ATOMIC_RELAXED, __HIP_MEMORY_SCOPE_AGENT); return RSM == 0 ? v : 1.0f / sqrtf(v * (1.f / DM) + EPS); }
;     __device__ __forceinline__ void operator()(const f32x4 (&acc)[2][2][4][2], const Unit& u, int wr, int wc, int fr, int fq) const {
;     ...
;             for (int m = 0; m < 4; ++m) { const int row = row0 + ai * HALF + m * 16; bf16* rowp = O + (size_t)row * ldc + col0; const float sc = row_scale<RSM>(rs, row);
;                 const f32x4 g0 = acc[ai][0][m][0] * sc, g1 = acc[ai][0][m][1] * sc, u0 = acc[ai][1][m][0] * sc, u1 = acc[ai][1][m][1] * sc;
;                 v4u w; w.x = pkbf(silu(g0[0]) * u0[0], silu(g0[1]) * u0[1]); w.y = pkbf(silu(g0[2]) * u0[2], silu(g0[3]) * u0[3]);
;                 w.z = pkbf(silu(g1[0]) * u1[0], silu(g1[1]) * u1[1]); w.w = pkbf(silu(g1[2]) * u1[2], silu(g1[3]) * u1[3]);
;                 *(v4u*)rowp = w; }
	v_mul_f32_e32 v84, 0xbfb8aa3b, v78
	v_mul_f32_e32 v85, 0xbfb8aa3b, v79
	v_mul_f32_e32 v86, 0xbfb8aa3b, v72
	v_mul_f32_e32 v87, 0xbfb8aa3b, v73
	v_mul_f32_e32 v88, 0xbfb8aa3b, v74
	v_mul_f32_e32 v89, 0xbfb8aa3b, v75
	v_exp_f32_e32 v82, v82
	v_exp_f32_e32 v83, v83
	v_exp_f32_e32 v84, v84
	v_exp_f32_e32 v85, v85
	v_exp_f32_e32 v86, v86
	v_exp_f32_e32 v87, v87
	v_exp_f32_e32 v88, v88
	v_exp_f32_e32 v89, v89
	v_add_f32_e32 v82, 1.0, v82
	v_add_f32_e32 v83, 1.0, v83
	v_add_f32_e32 v84, 1.0, v84
	v_add_f32_e32 v85, 1.0, v85
	v_add_f32_e32 v86, 1.0, v86
	v_add_f32_e32 v87, 1.0, v87
	v_add_f32_e32 v88, 1.0, v88
	v_add_f32_e32 v89, 1.0, v89
	v_rcp_f32_e32 v82, v82
	v_rcp_f32_e32 v83, v83
	v_rcp_f32_e32 v84, v84
	v_rcp_f32_e32 v85, v85
	v_rcp_f32_e32 v86, v86
	v_rcp_f32_e32 v87, v87
	v_rcp_f32_e32 v88, v88
	v_rcp_f32_e32 v89, v89
	v_pk_mul_f32 v[76:77], v[76:77], v[82:83]
	v_pk_mul_f32 v[78:79], v[78:79], v[84:85]
	v_pk_mul_f32 v[72:73], v[72:73], v[86:87]
	v_pk_mul_f32 v[74:75], v[74:75], v[88:89]
	v_pk_mul_f32 v[68:69], v[68:69], v[76:77]
	v_pk_mul_f32 v[70:71], v[70:71], v[78:79]
	v_pk_mul_f32 v[72:73], v[64:65], v[72:73]
	v_pk_mul_f32 v[74:75], v[66:67], v[74:75]
	v_cvt_pk_bf16_f32 v64, v68, v69
	v_cvt_pk_bf16_f32 v65, v70, v71
	v_cvt_pk_bf16_f32 v66, v72, v73
	v_cvt_pk_bf16_f32 v67, v74, v75
	global_store_dwordx4 v[80:81], v[64:67], off
	s_nop 1
	v_add_u32_e32 v64, 0x80, v144
	v_mad_i64_i32 v[64:65], s[0:1], v64, s47, v[146:147]
	v_lshl_add_u64 v[64:65], v[64:65], 0, v[148:149]
	s_nop 0
	v_mov_b32_e32 v66, v252
	v_pk_mul_f32 v[62:63], v[62:63], v[66:67] op_sel_hi:[1,0]
	v_pk_mul_f32 v[60:61], v[60:61], v[66:67] op_sel_hi:[1,0]
	v_pk_mul_f32 v[58:59], v[58:59], v[66:67] op_sel_hi:[1,0]
	v_pk_mul_f32 v[56:57], v[56:57], v[66:67] op_sel_hi:[1,0]
	v_pk_mul_f32 v[54:55], v[54:55], v[66:67] op_sel_hi:[1,0]
	v_pk_mul_f32 v[52:53], v[52:53], v[66:67] op_sel_hi:[1,0]
	v_pk_mul_f32 v[50:51], v[50:51], v[66:67] op_sel_hi:[1,0]
	v_pk_mul_f32 v[48:49], v[48:49], v[66:67] op_sel_hi:[1,0]
	v_mul_f32_e32 v66, 0xbfb8aa3b, v60
	v_mul_f32_e32 v67, 0xbfb8aa3b, v61
	v_mul_f32_e32 v68, 0xbfb8aa3b, v62
	v_mul_f32_e32 v69, 0xbfb8aa3b, v63
	v_mul_f32_e32 v70, 0xbfb8aa3b, v56
	v_mul_f32_e32 v71, 0xbfb8aa3b, v57
	v_mul_f32_e32 v72, 0xbfb8aa3b, v58
	v_mul_f32_e32 v73, 0xbfb8aa3b, v59
	v_exp_f32_e32 v66, v66
	v_exp_f32_e32 v67, v67
	v_exp_f32_e32 v68, v68
	v_exp_f32_e32 v69, v69
	v_exp_f32_e32 v70, v70
	v_exp_f32_e32 v71, v71
	v_exp_f32_e32 v72, v72
	v_exp_f32_e32 v73, v73
	v_add_f32_e32 v66, 1.0, v66
	v_add_f32_e32 v67, 1.0, v67
	v_add_f32_e32 v68, 1.0, v68
	v_add_f32_e32 v69, 1.0, v69
	v_add_f32_e32 v70, 1.0, v70
	v_add_f32_e32 v71, 1.0, v71
	v_add_f32_e32 v72, 1.0, v72
	v_add_f32_e32 v73, 1.0, v73
	v_rcp_f32_e32 v66, v66
	v_rcp_f32_e32 v67, v67
	v_rcp_f32_e32 v68, v68
	v_rcp_f32_e32 v69, v69
	v_rcp_f32_e32 v70, v70
	v_rcp_f32_e32 v71, v71
	v_rcp_f32_e32 v72, v72
	v_rcp_f32_e32 v73, v73
	v_pk_mul_f32 v[60:61], v[60:61], v[66:67]
	v_pk_mul_f32 v[62:63], v[62:63], v[68:69]
	v_pk_mul_f32 v[56:57], v[56:57], v[70:71]
	v_pk_mul_f32 v[58:59], v[58:59], v[72:73]
	v_pk_mul_f32 v[52:53], v[52:53], v[60:61]
	v_pk_mul_f32 v[54:55], v[54:55], v[62:63]
	v_pk_mul_f32 v[56:57], v[48:49], v[56:57]
	v_pk_mul_f32 v[58:59], v[50:51], v[58:59]
	v_cvt_pk_bf16_f32 v48, v52, v53
	v_cvt_pk_bf16_f32 v49, v54, v55
	v_cvt_pk_bf16_f32 v50, v56, v57
	v_cvt_pk_bf16_f32 v51, v58, v59
	global_store_dwordx4 v[64:65], v[48:51], off
	s_nop 1
	v_add_u32_e32 v48, 0x90, v144
	v_mad_i64_i32 v[48:49], s[0:1], v48, s47, v[146:147]
	v_lshl_add_u64 v[48:49], v[48:49], 0, v[148:149]
	s_nop 0
	v_mov_b32_e32 v50, v253
	v_pk_mul_f32 v[46:47], v[46:47], v[50:51] op_sel_hi:[1,0]
	v_pk_mul_f32 v[44:45], v[44:45], v[50:51] op_sel_hi:[1,0]
	v_pk_mul_f32 v[42:43], v[42:43], v[50:51] op_sel_hi:[1,0]
	v_pk_mul_f32 v[40:41], v[40:41], v[50:51] op_sel_hi:[1,0]
	v_pk_mul_f32 v[38:39], v[38:39], v[50:51] op_sel_hi:[1,0]
	v_pk_mul_f32 v[36:37], v[36:37], v[50:51] op_sel_hi:[1,0]
	v_pk_mul_f32 v[34:35], v[34:35], v[50:51] op_sel_hi:[1,0]
	v_pk_mul_f32 v[32:33], v[32:33], v[50:51] op_sel_hi:[1,0]
	v_mul_f32_e32 v50, 0xbfb8aa3b, v44
	v_mul_f32_e32 v51, 0xbfb8aa3b, v45
	v_mul_f32_e32 v52, 0xbfb8aa3b, v46
	v_mul_f32_e32 v53, 0xbfb8aa3b, v47
	v_mul_f32_e32 v54, 0xbfb8aa3b, v40
	v_mul_f32_e32 v55, 0xbfb8aa3b, v41
	v_mul_f32_e32 v56, 0xbfb8aa3b, v42
	v_mul_f32_e32 v57, 0xbfb8aa3b, v43
	v_exp_f32_e32 v50, v50
	v_exp_f32_e32 v51, v51
	v_exp_f32_e32 v52, v52
	v_exp_f32_e32 v53, v53
	v_exp_f32_e32 v54, v54
	v_exp_f32_e32 v55, v55
	v_exp_f32_e32 v56, v56
	v_exp_f32_e32 v57, v57
	v_add_f32_e32 v50, 1.0, v50
	v_add_f32_e32 v51, 1.0, v51
	v_add_f32_e32 v52, 1.0, v52
	v_add_f32_e32 v53, 1.0, v53
	v_add_f32_e32 v54, 1.0, v54
	v_add_f32_e32 v55, 1.0, v55
	v_add_f32_e32 v56, 1.0, v56
	v_add_f32_e32 v57, 1.0, v57
	v_rcp_f32_e32 v50, v50
	v_rcp_f32_e32 v51, v51
	v_rcp_f32_e32 v52, v52
	v_rcp_f32_e32 v53, v53
; #define PG8_BAR __builtin_amdgcn_s_barrier()
; __device__ __forceinline__ float silu(float x) { return x * sigm(x); }
; __device__ __forceinline__ unsigned pkbf(float lo, float hi) { const f32x2_m v = {lo, hi}; const bf16x2_m b = __builtin_convertvector(v, bf16x2_m); return __builtin_bit_cast(unsigned, b); }
; template <int RSM> __device__ __forceinline__ float row_scale(const float* p, int row) { const float v = __hip_atomic_load(p + row, __ATOMIC_RELAXED, __HIP_MEMORY_SCOPE_AGENT); return RSM == 0 ? v : 1.0f / sqrtf(v * (1.f / DM) + EPS); }
; template <class Epi, class Sched, bool ALIGN_EPI = false, bool SP2 = false>
; __device__ __forceinline__ void gemm_phase(PG8_LAS unsigned char* lds, const Gemm g, const Sched& S, const Epi& E) {
;     ...
;         if constexpr (ALIGN_EPI) { if (wr == 0) PG8_BAR; }
;         if constexpr (!Epi::AFTER_DRAIN) { E(acc, cur, wr, wc, fr, fq); S.done(cur); }
;         if (!has_next) break;
; #pragma unroll
;         for (int a = 0; a < 2; ++a)
; #pragma unroll
;             for (int b = 0; b < 2; ++b)
; #pragma unroll
;                 for (int m = 0; m < 4; ++m)
; #pragma unroll
;                     for (int n = 0; n < 2; ++n) acc[a][b][m][n] = (f32x4){0.f, 0.f, 0.f, 0.f};
;         cur = nxt; cA = nA; cB = nB; ++ui;
;         if constexpr (ALIGN_EPI) { if (wr == 1) PG8_BAR; }
;     __device__ __forceinline__ void operator()(const f32x4 (&acc)[2][2][4][2], const Unit& u, int wr, int wc, int fr, int fq) const {
;     ...
;             for (int m = 0; m < 4; ++m) { const int row = row0 + ai * HALF + m * 16; bf16* rowp = O + (size_t)row * ldc + col0; const float sc = row_scale<RSM>(rs, row);
;                 const f32x4 g0 = acc[ai][0][m][0] * sc, g1 = acc[ai][0][m][1] * sc, u0 = acc[ai][1][m][0] * sc, u1 = acc[ai][1][m][1] * sc;
;                 v4u w; w.x = pkbf(silu(g0[0]) * u0[0], silu(g0[1]) * u0[1]); w.y = pkbf(silu(g0[2]) * u0[2], silu(g0[3]) * u0[3]);
;                 w.z = pkbf(silu(g1[0]) * u1[0], silu(g1[1]) * u1[1]); w.w = pkbf(silu(g1[2]) * u1[2], silu(g1[3]) * u1[3]);
;                 *(v4u*)rowp = w; }
	v_rcp_f32_e32 v54, v54
	v_rcp_f32_e32 v55, v55
	v_rcp_f32_e32 v56, v56
	v_rcp_f32_e32 v57, v57
	v_pk_mul_f32 v[44:45], v[44:45], v[50:51]
	v_pk_mul_f32 v[46:47], v[46:47], v[52:53]
	v_pk_mul_f32 v[40:41], v[40:41], v[54:55]
	v_pk_mul_f32 v[42:43], v[42:43], v[56:57]
	v_pk_mul_f32 v[36:37], v[36:37], v[44:45]
	v_pk_mul_f32 v[38:39], v[38:39], v[46:47]
	v_pk_mul_f32 v[40:41], v[32:33], v[40:41]
	v_pk_mul_f32 v[42:43], v[34:35], v[42:43]
	v_cvt_pk_bf16_f32 v32, v36, v37
	v_cvt_pk_bf16_f32 v33, v38, v39
	v_cvt_pk_bf16_f32 v34, v40, v41
	v_cvt_pk_bf16_f32 v35, v42, v43
	global_store_dwordx4 v[48:49], v[32:35], off
	s_nop 1
	v_add_u32_e32 v32, 0xa0, v144
	v_mad_i64_i32 v[32:33], s[0:1], v32, s47, v[146:147]
	v_lshl_add_u64 v[32:33], v[32:33], 0, v[148:149]
	s_nop 0
	v_mov_b32_e32 v34, v254
	v_pk_mul_f32 v[30:31], v[30:31], v[34:35] op_sel_hi:[1,0]
	v_pk_mul_f32 v[28:29], v[28:29], v[34:35] op_sel_hi:[1,0]
	v_pk_mul_f32 v[26:27], v[26:27], v[34:35] op_sel_hi:[1,0]
	v_pk_mul_f32 v[24:25], v[24:25], v[34:35] op_sel_hi:[1,0]
	v_pk_mul_f32 v[22:23], v[22:23], v[34:35] op_sel_hi:[1,0]
	v_pk_mul_f32 v[20:21], v[20:21], v[34:35] op_sel_hi:[1,0]
	v_pk_mul_f32 v[18:19], v[18:19], v[34:35] op_sel_hi:[1,0]
	v_pk_mul_f32 v[16:17], v[16:17], v[34:35] op_sel_hi:[1,0]
	v_mul_f32_e32 v34, 0xbfb8aa3b, v28
	v_mul_f32_e32 v35, 0xbfb8aa3b, v29
	v_mul_f32_e32 v36, 0xbfb8aa3b, v30
	v_mul_f32_e32 v37, 0xbfb8aa3b, v31
	v_mul_f32_e32 v38, 0xbfb8aa3b, v24
	v_mul_f32_e32 v39, 0xbfb8aa3b, v25
	v_mul_f32_e32 v40, 0xbfb8aa3b, v26
	v_mul_f32_e32 v41, 0xbfb8aa3b, v27
	v_exp_f32_e32 v34, v34
	v_exp_f32_e32 v35, v35
	v_exp_f32_e32 v36, v36
	v_exp_f32_e32 v37, v37
	v_exp_f32_e32 v38, v38
	v_exp_f32_e32 v39, v39
	v_exp_f32_e32 v40, v40
	v_exp_f32_e32 v41, v41
	v_add_f32_e32 v34, 1.0, v34
	v_add_f32_e32 v35, 1.0, v35
	v_add_f32_e32 v36, 1.0, v36
	v_add_f32_e32 v37, 1.0, v37
	v_add_f32_e32 v38, 1.0, v38
	v_add_f32_e32 v39, 1.0, v39
	v_add_f32_e32 v40, 1.0, v40
	v_add_f32_e32 v41, 1.0, v41
	v_rcp_f32_e32 v34, v34
	v_rcp_f32_e32 v35, v35
	v_rcp_f32_e32 v36, v36
	v_rcp_f32_e32 v37, v37
	v_rcp_f32_e32 v38, v38
	v_rcp_f32_e32 v39, v39
	v_rcp_f32_e32 v40, v40
	v_rcp_f32_e32 v41, v41
	v_pk_mul_f32 v[28:29], v[28:29], v[34:35]
	v_pk_mul_f32 v[30:31], v[30:31], v[36:37]
	v_pk_mul_f32 v[24:25], v[24:25], v[38:39]
	v_pk_mul_f32 v[26:27], v[26:27], v[40:41]
	v_pk_mul_f32 v[20:21], v[20:21], v[28:29]
	v_pk_mul_f32 v[22:23], v[22:23], v[30:31]
	v_pk_mul_f32 v[24:25], v[16:17], v[24:25]
	v_pk_mul_f32 v[26:27], v[18:19], v[26:27]
	v_cvt_pk_bf16_f32 v16, v20, v21
	v_cvt_pk_bf16_f32 v17, v22, v23
	v_cvt_pk_bf16_f32 v18, v24, v25
	v_cvt_pk_bf16_f32 v19, v26, v27
	global_store_dwordx4 v[32:33], v[16:19], off
	s_nop 1
	v_add_u32_e32 v17, 0xb0, v144
	v_mad_i64_i32 v[16:17], s[0:1], v17, s47, v[146:147]
	v_lshl_add_u64 v[16:17], v[16:17], 0, v[148:149]
	s_mov_b64 s[0:1], -1
	v_mov_b32_e32 v18, v255
	v_pk_mul_f32 v[14:15], v[14:15], v[18:19] op_sel_hi:[1,0]
	v_pk_mul_f32 v[12:13], v[12:13], v[18:19] op_sel_hi:[1,0]
	v_pk_mul_f32 v[10:11], v[10:11], v[18:19] op_sel_hi:[1,0]
	v_pk_mul_f32 v[8:9], v[8:9], v[18:19] op_sel_hi:[1,0]
	v_pk_mul_f32 v[6:7], v[6:7], v[18:19] op_sel_hi:[1,0]
	v_pk_mul_f32 v[4:5], v[4:5], v[18:19] op_sel_hi:[1,0]
	v_pk_mul_f32 v[2:3], v[2:3], v[18:19] op_sel_hi:[1,0]
	v_pk_mul_f32 v[0:1], v[0:1], v[18:19] op_sel_hi:[1,0]
	v_mul_f32_e32 v18, 0xbfb8aa3b, v12
	v_mul_f32_e32 v19, 0xbfb8aa3b, v13
	v_mul_f32_e32 v20, 0xbfb8aa3b, v14
	v_mul_f32_e32 v21, 0xbfb8aa3b, v15
	v_mul_f32_e32 v22, 0xbfb8aa3b, v8
	v_mul_f32_e32 v23, 0xbfb8aa3b, v9
	v_mul_f32_e32 v24, 0xbfb8aa3b, v10
	v_mul_f32_e32 v25, 0xbfb8aa3b, v11
	v_exp_f32_e32 v18, v18
	v_exp_f32_e32 v19, v19
	v_exp_f32_e32 v20, v20
	v_exp_f32_e32 v21, v21
	v_exp_f32_e32 v22, v22
	v_exp_f32_e32 v23, v23
	v_exp_f32_e32 v24, v24
	v_exp_f32_e32 v25, v25
	v_add_f32_e32 v18, 1.0, v18
	v_add_f32_e32 v19, 1.0, v19
	v_add_f32_e32 v20, 1.0, v20
	v_add_f32_e32 v21, 1.0, v21
	v_add_f32_e32 v22, 1.0, v22
	v_add_f32_e32 v23, 1.0, v23
	v_add_f32_e32 v24, 1.0, v24
	v_add_f32_e32 v25, 1.0, v25
	v_rcp_f32_e32 v18, v18
	v_rcp_f32_e32 v19, v19
	v_rcp_f32_e32 v20, v20
	v_rcp_f32_e32 v21, v21
	v_rcp_f32_e32 v22, v22
	v_rcp_f32_e32 v23, v23
	v_rcp_f32_e32 v24, v24
	v_rcp_f32_e32 v25, v25
	v_pk_mul_f32 v[12:13], v[12:13], v[18:19]
	v_pk_mul_f32 v[14:15], v[14:15], v[20:21]
	v_pk_mul_f32 v[8:9], v[8:9], v[22:23]
	v_pk_mul_f32 v[10:11], v[10:11], v[24:25]
	v_pk_mul_f32 v[4:5], v[4:5], v[12:13]
	v_pk_mul_f32 v[6:7], v[6:7], v[14:15]
	v_pk_mul_f32 v[8:9], v[0:1], v[8:9]
	v_pk_mul_f32 v[10:11], v[2:3], v[10:11]
	s_andn2_b64 vcc, exec, s[4:5]
	v_cvt_pk_bf16_f32 v0, v4, v5
	v_cvt_pk_bf16_f32 v1, v6, v7
	v_cvt_pk_bf16_f32 v2, v8, v9
	v_cvt_pk_bf16_f32 v3, v10, v11
	global_store_dwordx4 v[16:17], v[0:3], off
	s_cbranch_vccnz .LBB0_1878
	s_andn2_b64 vcc, exec, s[10:11]
	s_cbranch_vccnz .LBB0_1877
	s_barrier
	s_branch .LBB0_1877

; __global__ void __launch_bounds__(512, 2) fwd_megakernel(Args a) {
	.amdhsa_kernel _Z14fwd_megakernel4Args
		.amdhsa_group_segment_fixed_size 0
		.amdhsa_private_segment_fixed_size 0
		.amdhsa_kernarg_size 432
		.amdhsa_user_sgpr_count 2
		.amdhsa_user_sgpr_dispatch_ptr 0
		.amdhsa_user_sgpr_queue_ptr 0
		.amdhsa_user_sgpr_kernarg_segment_ptr 1
		.amdhsa_user_sgpr_dispatch_id 0
		.amdhsa_user_sgpr_kernarg_preload_length 0
		.amdhsa_user_sgpr_kernarg_preload_offset 0
		.amdhsa_user_sgpr_private_segment_size 0
		.amdhsa_uses_dynamic_stack 0
		.amdhsa_enable_private_segment 0
		.amdhsa_system_sgpr_workgroup_id_x 1
		.amdhsa_system_sgpr_workgroup_id_y 0
		.amdhsa_system_sgpr_workgroup_id_z 0
		.amdhsa_system_sgpr_workgroup_info 0
		.amdhsa_system_vgpr_workitem_id 2
		.amdhsa_next_free_vgpr 256
		.amdhsa_next_free_sgpr 102
		.amdhsa_accum_offset 256
		.amdhsa_reserve_vcc 1
		.amdhsa_float_round_mode_32 0
		.amdhsa_float_round_mode_16_64 0
		.amdhsa_float_denorm_mode_32 3
		.amdhsa_float_denorm_mode_16_64 3
		.amdhsa_dx10_clamp 1
		.amdhsa_ieee_mode 1
		.amdhsa_fp16_overflow 0
		.amdhsa_tg_split 0
		.amdhsa_exception_fp_ieee_invalid_op 0
		.amdhsa_exception_fp_denorm_src 0
		.amdhsa_exception_fp_ieee_div_zero 0
		.amdhsa_exception_fp_ieee_overflow 0
		.amdhsa_exception_fp_ieee_underflow 0
		.amdhsa_exception_fp_ieee_inexact 0
		.amdhsa_exception_int_div_zero 0
	.end_amdhsa_kernel

; __global__ void __launch_bounds__(512, 2) fwd_megakernel(Args a) {
amdhsa.kernels:
  - .agpr_count:     0
    .args:
      - .offset:         0
        .size:           176
        .value_kind:     by_value
      - .offset:         176
        .size:           4
        .value_kind:     hidden_block_count_x
      - .offset:         180
        .size:           4
        .value_kind:     hidden_block_count_y
      - .offset:         184
        .size:           4
        .value_kind:     hidden_block_count_z
      - .offset:         188
        .size:           2
        .value_kind:     hidden_group_size_x
      - .offset:         190
        .size:           2
        .value_kind:     hidden_group_size_y
      - .offset:         192
        .size:           2
        .value_kind:     hidden_group_size_z
      - .offset:         194
        .size:           2
        .value_kind:     hidden_remainder_x
      - .offset:         196
        .size:           2
        .value_kind:     hidden_remainder_y
      - .offset:         198
        .size:           2
        .value_kind:     hidden_remainder_z
      - .offset:         216
        .size:           8
        .value_kind:     hidden_global_offset_x
      - .offset:         224
        .size:           8
        .value_kind:     hidden_global_offset_y
      - .offset:         232
        .size:           8
        .value_kind:     hidden_global_offset_z
      - .offset:         240
        .size:           2
        .value_kind:     hidden_grid_dims
      - .offset:         264
        .size:           8
        .value_kind:     hidden_multigrid_sync_arg
      - .offset:         296
        .size:           4
        .value_kind:     hidden_dynamic_lds_size
    .group_segment_fixed_size: 0
    .kernarg_segment_align: 8
    .kernarg_segment_size: 432
    .language:       OpenCL C
    .language_version:
      - 2
      - 0
    .max_flat_workgroup_size: 512
    .name:           _Z14fwd_megakernel4Args
    .private_segment_fixed_size: 0
    .sgpr_count:     108
    .sgpr_spill_count: 57
    .symbol:         _Z14fwd_megakernel4Args.kd
    .uniform_work_group_size: 1
    .uses_dynamic_stack: false
    .vgpr_count:     256
    .vgpr_spill_count: 0
    .wavefront_size: 64
